# P3 2nd epilogue + P4 epilogue: write-through (sc1) 8-byte tile stores widened to 16-byte via v_permlane16_swap_b32 pairs (32->16 stores each), cvt_pk redirected to fresh regs, all vmcnt waits re-deriv
# speedup vs baseline: 1.0175x; 1.0161x over previous
.LBB0_294:
	s_or_b64 exec, exec, s[6:7]
	s_waitcnt vmcnt(0)
	s_barrier
	v_mbcnt_lo_u32_b32 v242, -1, 0
	v_mbcnt_hi_u32_b32 v242, -1, v242
	v_bfe_u32 v242, v242, 4, 1
	v_mul_u32_u24_e32 v242, 24, v242
	v_mov_b32_e32 v243, 0
	s_nop 0
	v_ashrrev_i32_e32 v133, 31, v132
	v_lshlrev_b64 v[136:137], 12, v[132:133]
	v_ashrrev_i32_e32 v135, 31, v134
	v_lshlrev_b64 v[132:133], 11, v[132:133]
	v_lshl_add_u64 v[136:137], s[76:77], 0, v[136:137]
	v_lshlrev_b64 v[138:139], 1, v[134:135]
	v_lshl_add_u64 v[132:133], s[82:83], 0, v[132:133]
	v_lshl_add_u64 v[134:135], v[136:137], 0, v[138:139]
	v_lshl_add_u64 v[132:133], v[132:133], 0, v[138:139]
	global_load_dwordx2 v[170:171], v[132:133], off
	global_load_dwordx2 v[172:173], v[134:135], off offset:2048
	global_load_dwordx2 v[174:175], v[132:133], off offset:32
	global_load_dwordx2 v[176:177], v[134:135], off offset:2080
	global_load_dwordx2 v[178:179], v[132:133], off offset:64
	global_load_dwordx2 v[180:181], v[134:135], off offset:2112
	global_load_dwordx2 v[182:183], v[132:133], off offset:96
	global_load_dwordx2 v[184:185], v[134:135], off offset:2144
	global_load_dwordx2 v[186:187], v[134:135], off offset:2304
	global_load_dwordx2 v[188:189], v[134:135], off offset:2336
	global_load_dwordx2 v[190:191], v[134:135], off offset:2368
	global_load_dwordx2 v[192:193], v[134:135], off offset:2400
	global_load_dwordx2 v[194:195], v[132:133], off offset:256
	global_load_dwordx2 v[196:197], v[132:133], off offset:288
	global_load_dwordx2 v[198:199], v[132:133], off offset:320
	global_load_dwordx2 v[200:201], v[132:133], off offset:352
	v_add_co_u32_e64 v138, s[6:7], s11, v134
	s_waitcnt vmcnt(15)
	v_lshlrev_b32_e32 v130, 16, v170
	v_addc_co_u32_e64 v139, s[6:7], 0, v135, s[6:7]
	v_add_co_u32_e64 v136, s[6:7], s61, v132
	s_waitcnt vmcnt(14)
	v_lshlrev_b32_e32 v212, 16, v172
	v_addc_co_u32_e64 v137, s[6:7], 0, v133, s[6:7]
	global_load_dwordx2 v[202:203], v[138:139], off offset:2048
	global_load_dwordx2 v[204:205], v[138:139], off offset:2080
	global_load_dwordx2 v[158:159], v[138:139], off offset:2112
	global_load_dwordx2 v[154:155], v[138:139], off offset:2144
	global_load_dwordx2 v[206:207], v[136:137], off
	global_load_dwordx2 v[208:209], v[136:137], off offset:32
	global_load_dwordx2 v[210:211], v[136:137], off offset:64
	global_load_dwordx2 v[156:157], v[136:137], off offset:96
	global_load_dwordx2 v[150:151], v[138:139], off offset:2304
	global_load_dwordx2 v[146:147], v[138:139], off offset:2336
	global_load_dwordx2 v[142:143], v[138:139], off offset:2368
	s_nop 0
	global_load_dwordx2 v[138:139], v[138:139], off offset:2400
	s_nop 0
	global_load_dwordx2 v[152:153], v[136:137], off offset:256
	global_load_dwordx2 v[148:149], v[136:137], off offset:288
	global_load_dwordx2 v[144:145], v[136:137], off offset:320
	global_load_dwordx2 v[140:141], v[136:137], off offset:352
	v_and_b32_e32 v170, 0xffff0000, v170
	v_and_b32_e32 v172, 0xffff0000, v172
	v_lshlrev_b32_e32 v213, 16, v171
	v_lshlrev_b32_e32 v214, 16, v173
	v_and_b32_e32 v171, 0xffff0000, v171
	v_and_b32_e32 v173, 0xffff0000, v173
	s_waitcnt vmcnt(29)
	v_lshlrev_b32_e32 v215, 16, v174
	s_waitcnt vmcnt(28)
	v_lshlrev_b32_e32 v216, 16, v176
	v_and_b32_e32 v174, 0xffff0000, v174
	v_and_b32_e32 v176, 0xffff0000, v176
	v_lshlrev_b32_e32 v217, 16, v175
	v_lshlrev_b32_e32 v218, 16, v177
	v_and_b32_e32 v175, 0xffff0000, v175
	v_and_b32_e32 v177, 0xffff0000, v177
	s_waitcnt vmcnt(27)
	v_lshlrev_b32_e32 v219, 16, v178
	s_waitcnt vmcnt(26)
	v_lshlrev_b32_e32 v220, 16, v180
	v_and_b32_e32 v178, 0xffff0000, v178
	v_and_b32_e32 v180, 0xffff0000, v180
	v_lshlrev_b32_e32 v221, 16, v179
	v_lshlrev_b32_e32 v222, 16, v181
	v_and_b32_e32 v179, 0xffff0000, v179
	v_and_b32_e32 v181, 0xffff0000, v181
	v_fmac_f32_e32 v130, v122, v212
	v_fmac_f32_e32 v170, v123, v172
	v_fmac_f32_e32 v213, v124, v214
	v_fmac_f32_e32 v171, v125, v173
	v_fmac_f32_e32 v215, v126, v216
	v_fmac_f32_e32 v174, v127, v176
	v_fmac_f32_e32 v217, v128, v218
	v_fmac_f32_e32 v175, v129, v177
	v_fmac_f32_e32 v219, v118, v220
	v_fmac_f32_e32 v178, v119, v180
	v_fmac_f32_e32 v221, v120, v222
	v_fmac_f32_e32 v179, v121, v181
	v_cvt_pk_bf16_f32 v224, v130, v170
	v_cvt_pk_bf16_f32 v225, v213, v171
	v_cvt_pk_bf16_f32 v226, v215, v174
	v_cvt_pk_bf16_f32 v227, v217, v175
	v_cvt_pk_bf16_f32 v228, v219, v178
	v_cvt_pk_bf16_f32 v229, v221, v179
	s_waitcnt vmcnt(25)
	v_lshlrev_b32_e32 v118, 16, v182
	s_waitcnt vmcnt(24)
	v_lshlrev_b32_e32 v119, 16, v184
	v_fmac_f32_e32 v118, v106, v119
	v_and_b32_e32 v106, 0xffff0000, v182
	v_and_b32_e32 v119, 0xffff0000, v184
	v_fmac_f32_e32 v106, v107, v119
	v_lshlrev_b32_e32 v107, 16, v183
	v_lshlrev_b32_e32 v119, 16, v185
	v_fmac_f32_e32 v107, v108, v119
	v_and_b32_e32 v108, 0xffff0000, v183
	v_and_b32_e32 v119, 0xffff0000, v185
	v_fmac_f32_e32 v108, v109, v119
	v_cvt_pk_bf16_f32 v230, v118, v106
	v_cvt_pk_bf16_f32 v231, v107, v108
	s_nop 1
	v_permlane16_swap_b32_e32 v224, v226
	v_permlane16_swap_b32_e32 v225, v227
	v_permlane16_swap_b32_e32 v228, v230
	v_permlane16_swap_b32_e32 v229, v231
	v_lshl_add_u64 v[240:241], v[132:133], 0, v[242:243]
	global_store_dwordx4 v[240:241], v[224:227], off sc1
	global_store_dwordx4 v[240:241], v[228:231], off offset:64 sc1
	s_waitcnt vmcnt(21)
	v_lshlrev_b32_e32 v106, 16, v194
	v_lshlrev_b32_e32 v107, 16, v186
	v_fmac_f32_e32 v106, v114, v107
	v_and_b32_e32 v107, 0xffff0000, v194
	v_and_b32_e32 v108, 0xffff0000, v186
	v_fmac_f32_e32 v107, v115, v108
	v_lshlrev_b32_e32 v108, 16, v195
	v_lshlrev_b32_e32 v109, 16, v187
	v_fmac_f32_e32 v108, v116, v109
	v_and_b32_e32 v109, 0xffff0000, v195
	v_and_b32_e32 v114, 0xffff0000, v187
	v_fmac_f32_e32 v109, v117, v114
	v_cvt_pk_bf16_f32 v232, v106, v107
	v_cvt_pk_bf16_f32 v233, v108, v109
	s_waitcnt vmcnt(20)
	v_lshlrev_b32_e32 v106, 16, v196
	v_lshlrev_b32_e32 v107, 16, v188
	v_fmac_f32_e32 v106, v110, v107
	v_and_b32_e32 v107, 0xffff0000, v196
	v_and_b32_e32 v108, 0xffff0000, v188
	v_fmac_f32_e32 v107, v111, v108
	v_lshlrev_b32_e32 v108, 16, v197
	v_lshlrev_b32_e32 v109, 16, v189
	v_fmac_f32_e32 v108, v112, v109
	v_and_b32_e32 v109, 0xffff0000, v197
	v_and_b32_e32 v110, 0xffff0000, v189
	v_fmac_f32_e32 v109, v113, v110
	v_cvt_pk_bf16_f32 v234, v106, v107
	v_cvt_pk_bf16_f32 v235, v108, v109
	s_waitcnt vmcnt(19)
	v_lshlrev_b32_e32 v106, 16, v198
	v_lshlrev_b32_e32 v107, 16, v190
	v_fmac_f32_e32 v106, v102, v107
	v_and_b32_e32 v102, 0xffff0000, v198
	v_and_b32_e32 v107, 0xffff0000, v190
	v_fmac_f32_e32 v102, v103, v107
	v_lshlrev_b32_e32 v103, 16, v199
	v_lshlrev_b32_e32 v107, 16, v191
	v_fmac_f32_e32 v103, v104, v107
	v_and_b32_e32 v104, 0xffff0000, v199
	v_and_b32_e32 v107, 0xffff0000, v191
	v_fmac_f32_e32 v104, v105, v107
	v_cvt_pk_bf16_f32 v236, v106, v102
	v_cvt_pk_bf16_f32 v237, v103, v104
	s_waitcnt vmcnt(18)
	v_lshlrev_b32_e32 v102, 16, v200
	v_lshlrev_b32_e32 v103, 16, v192
	v_fmac_f32_e32 v102, v98, v103
	v_and_b32_e32 v98, 0xffff0000, v200
	v_and_b32_e32 v103, 0xffff0000, v192
	v_fmac_f32_e32 v98, v99, v103
	v_lshlrev_b32_e32 v99, 16, v201
	v_lshlrev_b32_e32 v103, 16, v193
	v_fmac_f32_e32 v99, v100, v103
	v_and_b32_e32 v100, 0xffff0000, v201
	v_and_b32_e32 v103, 0xffff0000, v193
	v_fmac_f32_e32 v100, v101, v103
	v_cvt_pk_bf16_f32 v238, v102, v98
	v_cvt_pk_bf16_f32 v239, v99, v100
	s_nop 1
	v_permlane16_swap_b32_e32 v232, v234
	v_permlane16_swap_b32_e32 v233, v235
	v_permlane16_swap_b32_e32 v236, v238
	v_permlane16_swap_b32_e32 v237, v239
	v_lshl_add_u64 v[240:241], v[132:133], 0, v[242:243]
	global_store_dwordx4 v[240:241], v[232:235], off offset:256 sc1
	global_store_dwordx4 v[240:241], v[236:239], off offset:320 sc1
	s_waitcnt vmcnt(15)
	v_lshlrev_b32_e32 v98, 16, v206
	v_lshlrev_b32_e32 v99, 16, v202
	v_fmac_f32_e32 v98, v94, v99
	v_and_b32_e32 v94, 0xffff0000, v206
	v_and_b32_e32 v99, 0xffff0000, v202
	v_fmac_f32_e32 v94, v95, v99
	v_lshlrev_b32_e32 v95, 16, v207
	v_lshlrev_b32_e32 v99, 16, v203
	v_fmac_f32_e32 v95, v96, v99
	v_and_b32_e32 v96, 0xffff0000, v207
	v_and_b32_e32 v99, 0xffff0000, v203
	v_fmac_f32_e32 v96, v97, v99
	v_cvt_pk_bf16_f32 v224, v98, v94
	v_cvt_pk_bf16_f32 v225, v95, v96
	s_waitcnt vmcnt(14)
	v_lshlrev_b32_e32 v94, 16, v208
	v_lshlrev_b32_e32 v95, 16, v204
	v_fmac_f32_e32 v94, v90, v95
	v_and_b32_e32 v90, 0xffff0000, v208
	v_and_b32_e32 v95, 0xffff0000, v204
	v_fmac_f32_e32 v90, v91, v95
	v_lshlrev_b32_e32 v91, 16, v209
	v_lshlrev_b32_e32 v95, 16, v205
	v_fmac_f32_e32 v91, v92, v95
	v_and_b32_e32 v92, 0xffff0000, v209
	v_and_b32_e32 v95, 0xffff0000, v205
	v_fmac_f32_e32 v92, v93, v95
	v_cvt_pk_bf16_f32 v226, v94, v90
	v_cvt_pk_bf16_f32 v227, v91, v92
	s_waitcnt vmcnt(13)
	v_lshlrev_b32_e32 v90, 16, v210
	v_lshlrev_b32_e32 v91, 16, v158
	v_fmac_f32_e32 v90, v82, v91
	v_and_b32_e32 v82, 0xffff0000, v210
	v_and_b32_e32 v91, 0xffff0000, v158
	v_fmac_f32_e32 v82, v83, v91
	v_lshlrev_b32_e32 v83, 16, v211
	v_lshlrev_b32_e32 v91, 16, v159
	v_fmac_f32_e32 v83, v84, v91
	v_and_b32_e32 v84, 0xffff0000, v211
	v_and_b32_e32 v91, 0xffff0000, v159
	v_fmac_f32_e32 v84, v85, v91
	v_cvt_pk_bf16_f32 v228, v90, v82
	v_cvt_pk_bf16_f32 v229, v83, v84
	s_waitcnt vmcnt(12)
	v_lshlrev_b32_e32 v82, 16, v156
	v_lshlrev_b32_e32 v83, 16, v154
	v_fmac_f32_e32 v82, v74, v83
	v_and_b32_e32 v74, 0xffff0000, v156
	v_and_b32_e32 v83, 0xffff0000, v154
	v_fmac_f32_e32 v74, v75, v83
	v_lshlrev_b32_e32 v75, 16, v157
	v_lshlrev_b32_e32 v83, 16, v155
	v_fmac_f32_e32 v75, v76, v83
	v_and_b32_e32 v76, 0xffff0000, v157
	v_and_b32_e32 v83, 0xffff0000, v155
	v_fmac_f32_e32 v76, v77, v83
	v_cvt_pk_bf16_f32 v230, v82, v74
	v_cvt_pk_bf16_f32 v231, v75, v76
	s_nop 1
	v_permlane16_swap_b32_e32 v224, v226
	v_permlane16_swap_b32_e32 v225, v227
	v_permlane16_swap_b32_e32 v228, v230
	v_permlane16_swap_b32_e32 v229, v231
	v_lshl_add_u64 v[240:241], v[136:137], 0, v[242:243]
	global_store_dwordx4 v[240:241], v[224:227], off sc1
	global_store_dwordx4 v[240:241], v[228:231], off offset:64 sc1
	s_waitcnt vmcnt(9)
	v_lshlrev_b32_e32 v74, 16, v152
	v_lshlrev_b32_e32 v75, 16, v150
	v_fmac_f32_e32 v74, v86, v75
	v_and_b32_e32 v75, 0xffff0000, v152
	v_and_b32_e32 v76, 0xffff0000, v150
	v_fmac_f32_e32 v75, v87, v76
	v_lshlrev_b32_e32 v76, 16, v153
	v_lshlrev_b32_e32 v77, 16, v151
	v_fmac_f32_e32 v76, v88, v77
	v_and_b32_e32 v77, 0xffff0000, v153
	v_and_b32_e32 v82, 0xffff0000, v151
	v_fmac_f32_e32 v77, v89, v82
	v_cvt_pk_bf16_f32 v232, v74, v75
	v_cvt_pk_bf16_f32 v233, v76, v77
	s_waitcnt vmcnt(8)
	v_lshlrev_b32_e32 v74, 16, v148
	v_lshlrev_b32_e32 v75, 16, v146
	v_fmac_f32_e32 v74, v78, v75
	v_and_b32_e32 v75, 0xffff0000, v148
	v_and_b32_e32 v76, 0xffff0000, v146
	v_fmac_f32_e32 v75, v79, v76
	v_lshlrev_b32_e32 v76, 16, v149
	v_lshlrev_b32_e32 v77, 16, v147
	v_fmac_f32_e32 v76, v80, v77
	v_and_b32_e32 v77, 0xffff0000, v149
	v_and_b32_e32 v78, 0xffff0000, v147
	v_fmac_f32_e32 v77, v81, v78
	v_cvt_pk_bf16_f32 v234, v74, v75
	v_cvt_pk_bf16_f32 v235, v76, v77
	s_waitcnt vmcnt(7)
	v_lshlrev_b32_e32 v74, 16, v144
	v_lshlrev_b32_e32 v75, 16, v142
	v_fmac_f32_e32 v74, v70, v75
	v_and_b32_e32 v70, 0xffff0000, v144
	v_and_b32_e32 v75, 0xffff0000, v142
	v_fmac_f32_e32 v70, v71, v75
	v_lshlrev_b32_e32 v71, 16, v145
	v_lshlrev_b32_e32 v75, 16, v143
	v_fmac_f32_e32 v71, v72, v75
	v_and_b32_e32 v72, 0xffff0000, v145
	v_and_b32_e32 v75, 0xffff0000, v143
	v_fmac_f32_e32 v72, v73, v75
	v_cvt_pk_bf16_f32 v236, v74, v70
	v_cvt_pk_bf16_f32 v237, v71, v72
	s_waitcnt vmcnt(6)
	v_lshlrev_b32_e32 v70, 16, v140
	v_lshlrev_b32_e32 v71, 16, v138
	v_fmac_f32_e32 v70, v66, v71
	v_and_b32_e32 v66, 0xffff0000, v140
	v_and_b32_e32 v71, 0xffff0000, v138
	v_fmac_f32_e32 v66, v67, v71
	v_lshlrev_b32_e32 v67, 16, v141
	v_lshlrev_b32_e32 v71, 16, v139
	v_fmac_f32_e32 v67, v68, v71
	v_and_b32_e32 v68, 0xffff0000, v141
	v_and_b32_e32 v71, 0xffff0000, v139
	v_fmac_f32_e32 v68, v69, v71
	v_cvt_pk_bf16_f32 v238, v70, v66
	v_cvt_pk_bf16_f32 v239, v67, v68
	s_nop 1
	v_permlane16_swap_b32_e32 v232, v234
	v_permlane16_swap_b32_e32 v233, v235
	v_permlane16_swap_b32_e32 v236, v238
	v_permlane16_swap_b32_e32 v237, v239
	v_lshl_add_u64 v[240:241], v[136:137], 0, v[242:243]
	global_store_dwordx4 v[240:241], v[232:235], off offset:256 sc1
	global_store_dwordx4 v[240:241], v[236:239], off offset:320 sc1
	v_add_co_u32_e64 v68, s[6:7], s62, v134
	s_nop 1
	v_addc_co_u32_e64 v69, s[6:7], 0, v135, s[6:7]
	v_add_co_u32_e64 v90, s[6:7], s64, v132
	s_nop 1
	v_addc_co_u32_e64 v91, s[6:7], 0, v133, s[6:7]
	global_load_dwordx2 v[92:93], v[90:91], off
	global_load_dwordx2 v[94:95], v[68:69], off offset:2048
	global_load_dwordx2 v[96:97], v[90:91], off offset:32
	global_load_dwordx2 v[98:99], v[68:69], off offset:2080
	global_load_dwordx2 v[100:101], v[90:91], off offset:64
	global_load_dwordx2 v[102:103], v[68:69], off offset:2112
	global_load_dwordx2 v[104:105], v[90:91], off offset:96
	global_load_dwordx2 v[106:107], v[68:69], off offset:2144
	v_add_co_u32_e64 v70, s[6:7], s63, v134
	s_waitcnt vmcnt(7)
	v_lshlrev_b32_e32 v130, 16, v92
	v_addc_co_u32_e64 v71, s[6:7], 0, v135, s[6:7]
	v_add_co_u32_e64 v66, s[6:7], s65, v132
	s_waitcnt vmcnt(6)
	v_lshlrev_b32_e32 v136, 16, v94
	v_addc_co_u32_e64 v67, s[6:7], 0, v133, s[6:7]
	global_load_dwordx2 v[108:109], v[68:69], off offset:2304
	global_load_dwordx2 v[110:111], v[68:69], off offset:2336
	global_load_dwordx2 v[112:113], v[68:69], off offset:2368
	global_load_dwordx2 v[114:115], v[68:69], off offset:2400
	global_load_dwordx2 v[116:117], v[90:91], off offset:256
	global_load_dwordx2 v[118:119], v[90:91], off offset:288
	global_load_dwordx2 v[120:121], v[90:91], off offset:320
	global_load_dwordx2 v[122:123], v[90:91], off offset:352
	global_load_dwordx2 v[124:125], v[70:71], off offset:2048
	global_load_dwordx2 v[126:127], v[70:71], off offset:2080
	global_load_dwordx2 v[88:89], v[70:71], off offset:2112
	global_load_dwordx2 v[84:85], v[70:71], off offset:2144
	global_load_dwordx2 v[128:129], v[66:67], off
	global_load_dwordx2 v[132:133], v[66:67], off offset:32
	global_load_dwordx2 v[134:135], v[66:67], off offset:64
	global_load_dwordx2 v[86:87], v[66:67], off offset:96
	global_load_dwordx2 v[80:81], v[70:71], off offset:2304
	global_load_dwordx2 v[76:77], v[70:71], off offset:2336
	global_load_dwordx2 v[72:73], v[70:71], off offset:2368
	global_load_dwordx2 v[68:69], v[70:71], off offset:2400
	global_load_dwordx2 v[82:83], v[66:67], off offset:256
	global_load_dwordx2 v[78:79], v[66:67], off offset:288
	global_load_dwordx2 v[74:75], v[66:67], off offset:320
	s_nop 0
	global_load_dwordx2 v[70:71], v[66:67], off offset:352
	v_and_b32_e32 v92, 0xffff0000, v92
	v_and_b32_e32 v94, 0xffff0000, v94
	v_lshlrev_b32_e32 v137, 16, v93
	v_lshlrev_b32_e32 v138, 16, v95
	v_and_b32_e32 v93, 0xffff0000, v93
	v_and_b32_e32 v95, 0xffff0000, v95
	s_waitcnt vmcnt(29)
	v_lshlrev_b32_e32 v139, 16, v96
	s_waitcnt vmcnt(28)
	v_lshlrev_b32_e32 v140, 16, v98
	v_and_b32_e32 v96, 0xffff0000, v96
	v_and_b32_e32 v98, 0xffff0000, v98
	v_lshlrev_b32_e32 v141, 16, v97
	v_lshlrev_b32_e32 v142, 16, v99
	v_and_b32_e32 v97, 0xffff0000, v97
	v_and_b32_e32 v99, 0xffff0000, v99
	s_waitcnt vmcnt(27)
	v_lshlrev_b32_e32 v143, 16, v100
	s_waitcnt vmcnt(26)
	v_lshlrev_b32_e32 v144, 16, v102
	v_and_b32_e32 v100, 0xffff0000, v100
	v_and_b32_e32 v102, 0xffff0000, v102
	v_fmac_f32_e32 v130, v58, v136
	v_fmac_f32_e32 v92, v59, v94
	v_fmac_f32_e32 v137, v60, v138
	v_fmac_f32_e32 v93, v61, v95
	v_fmac_f32_e32 v139, v62, v140
	v_fmac_f32_e32 v96, v63, v98
	v_fmac_f32_e32 v141, v64, v142
	v_fmac_f32_e32 v97, v65, v99
	v_fmac_f32_e32 v143, v54, v144
	v_fmac_f32_e32 v100, v55, v102
	v_cvt_pk_bf16_f32 v224, v130, v92
	v_cvt_pk_bf16_f32 v225, v137, v93
	v_lshlrev_b32_e32 v145, 16, v101
	v_cvt_pk_bf16_f32 v226, v139, v96
	v_cvt_pk_bf16_f32 v227, v141, v97
	v_lshlrev_b32_e32 v54, 16, v103
	v_fmac_f32_e32 v145, v56, v54
	v_and_b32_e32 v55, 0xffff0000, v101
	v_and_b32_e32 v54, 0xffff0000, v103
	v_fmac_f32_e32 v55, v57, v54
	v_cvt_pk_bf16_f32 v228, v143, v100
	v_cvt_pk_bf16_f32 v229, v145, v55
	s_waitcnt vmcnt(25)
	v_lshlrev_b32_e32 v54, 16, v104
	s_waitcnt vmcnt(24)
	v_lshlrev_b32_e32 v55, 16, v106
	v_fmac_f32_e32 v54, v46, v55
	v_and_b32_e32 v46, 0xffff0000, v104
	v_and_b32_e32 v55, 0xffff0000, v106
	v_fmac_f32_e32 v46, v47, v55
	v_lshlrev_b32_e32 v47, 16, v105
	v_lshlrev_b32_e32 v55, 16, v107
	v_fmac_f32_e32 v47, v48, v55
	v_and_b32_e32 v48, 0xffff0000, v105
	v_and_b32_e32 v55, 0xffff0000, v107
	v_fmac_f32_e32 v48, v49, v55
	v_cvt_pk_bf16_f32 v230, v54, v46
	v_cvt_pk_bf16_f32 v231, v47, v48
	s_nop 1
	v_permlane16_swap_b32_e32 v224, v226
	v_permlane16_swap_b32_e32 v225, v227
	v_permlane16_swap_b32_e32 v228, v230
	v_permlane16_swap_b32_e32 v229, v231
	v_lshl_add_u64 v[240:241], v[90:91], 0, v[242:243]
	global_store_dwordx4 v[240:241], v[224:227], off sc1
	global_store_dwordx4 v[240:241], v[228:231], off offset:64 sc1
	s_waitcnt vmcnt(25)
	v_lshlrev_b32_e32 v47, 16, v108
	v_and_b32_e32 v48, 0xffff0000, v108
	v_lshlrev_b32_e32 v49, 16, v109
	s_waitcnt vmcnt(21)
	v_lshlrev_b32_e32 v46, 16, v116
	v_fmac_f32_e32 v46, v50, v47
	v_and_b32_e32 v47, 0xffff0000, v116
	v_fmac_f32_e32 v47, v51, v48
	v_lshlrev_b32_e32 v48, 16, v117
	v_fmac_f32_e32 v48, v52, v49
	v_and_b32_e32 v49, 0xffff0000, v117
	v_and_b32_e32 v50, 0xffff0000, v109
	v_fmac_f32_e32 v49, v53, v50
	v_cvt_pk_bf16_f32 v232, v46, v47
	v_cvt_pk_bf16_f32 v233, v48, v49
	s_waitcnt vmcnt(20)
	v_lshlrev_b32_e32 v46, 16, v118
	v_lshlrev_b32_e32 v47, 16, v110
	v_fmac_f32_e32 v46, v42, v47
	v_and_b32_e32 v42, 0xffff0000, v118
	v_and_b32_e32 v47, 0xffff0000, v110
	v_fmac_f32_e32 v42, v43, v47
	v_lshlrev_b32_e32 v43, 16, v119
	v_lshlrev_b32_e32 v47, 16, v111
	v_fmac_f32_e32 v43, v44, v47
	v_and_b32_e32 v44, 0xffff0000, v119
	v_and_b32_e32 v47, 0xffff0000, v111
	v_fmac_f32_e32 v44, v45, v47
	v_cvt_pk_bf16_f32 v234, v46, v42
	v_cvt_pk_bf16_f32 v235, v43, v44
	s_waitcnt vmcnt(19)
	v_lshlrev_b32_e32 v42, 16, v120
	v_lshlrev_b32_e32 v43, 16, v112
	v_fmac_f32_e32 v42, v38, v43
	v_and_b32_e32 v38, 0xffff0000, v120
	v_and_b32_e32 v43, 0xffff0000, v112
	v_fmac_f32_e32 v38, v39, v43
	v_lshlrev_b32_e32 v39, 16, v121
	v_lshlrev_b32_e32 v43, 16, v113
	v_fmac_f32_e32 v39, v40, v43
	v_and_b32_e32 v40, 0xffff0000, v121
	v_and_b32_e32 v43, 0xffff0000, v113
	v_fmac_f32_e32 v40, v41, v43
	v_cvt_pk_bf16_f32 v236, v42, v38
	v_cvt_pk_bf16_f32 v237, v39, v40
	s_waitcnt vmcnt(18)
	v_lshlrev_b32_e32 v38, 16, v122
	v_lshlrev_b32_e32 v39, 16, v114
	v_fmac_f32_e32 v38, v34, v39
	v_and_b32_e32 v34, 0xffff0000, v122
	v_and_b32_e32 v39, 0xffff0000, v114
	v_fmac_f32_e32 v34, v35, v39
	v_lshlrev_b32_e32 v35, 16, v123
	v_lshlrev_b32_e32 v39, 16, v115
	v_fmac_f32_e32 v35, v36, v39
	v_and_b32_e32 v36, 0xffff0000, v123
	v_and_b32_e32 v39, 0xffff0000, v115
	v_fmac_f32_e32 v36, v37, v39
	v_cvt_pk_bf16_f32 v238, v38, v34
	v_cvt_pk_bf16_f32 v239, v35, v36
	s_nop 1
	v_permlane16_swap_b32_e32 v232, v234
	v_permlane16_swap_b32_e32 v233, v235
	v_permlane16_swap_b32_e32 v236, v238
	v_permlane16_swap_b32_e32 v237, v239
	v_lshl_add_u64 v[240:241], v[90:91], 0, v[242:243]
	global_store_dwordx4 v[240:241], v[232:235], off offset:256 sc1
	global_store_dwordx4 v[240:241], v[236:239], off offset:320 sc1
	s_waitcnt vmcnt(15)
	v_lshlrev_b32_e32 v34, 16, v128
	v_lshlrev_b32_e32 v35, 16, v124
	v_fmac_f32_e32 v34, v30, v35
	v_and_b32_e32 v30, 0xffff0000, v128
	v_and_b32_e32 v35, 0xffff0000, v124
	v_fmac_f32_e32 v30, v31, v35
	v_lshlrev_b32_e32 v31, 16, v129
	v_lshlrev_b32_e32 v35, 16, v125
	v_fmac_f32_e32 v31, v32, v35
	v_and_b32_e32 v32, 0xffff0000, v129
	v_and_b32_e32 v35, 0xffff0000, v125
	v_fmac_f32_e32 v32, v33, v35
	v_cvt_pk_bf16_f32 v224, v34, v30
	v_cvt_pk_bf16_f32 v225, v31, v32
	s_waitcnt vmcnt(14)
	v_lshlrev_b32_e32 v30, 16, v132
	v_lshlrev_b32_e32 v31, 16, v126
	v_fmac_f32_e32 v30, v26, v31
	v_and_b32_e32 v26, 0xffff0000, v132
	v_and_b32_e32 v31, 0xffff0000, v126
	v_fmac_f32_e32 v26, v27, v31
	v_lshlrev_b32_e32 v27, 16, v133
	v_lshlrev_b32_e32 v31, 16, v127
	v_fmac_f32_e32 v27, v28, v31
	v_and_b32_e32 v28, 0xffff0000, v133
	v_and_b32_e32 v31, 0xffff0000, v127
	v_fmac_f32_e32 v28, v29, v31
	v_cvt_pk_bf16_f32 v226, v30, v26
	v_cvt_pk_bf16_f32 v227, v27, v28
	s_waitcnt vmcnt(13)
	v_lshlrev_b32_e32 v26, 16, v134
	v_lshlrev_b32_e32 v27, 16, v88
	v_fmac_f32_e32 v26, v22, v27
	v_and_b32_e32 v22, 0xffff0000, v134
	v_and_b32_e32 v27, 0xffff0000, v88
	v_fmac_f32_e32 v22, v23, v27
	v_lshlrev_b32_e32 v23, 16, v135
	v_lshlrev_b32_e32 v27, 16, v89
	v_fmac_f32_e32 v23, v24, v27
	v_and_b32_e32 v24, 0xffff0000, v135
	v_and_b32_e32 v27, 0xffff0000, v89
	v_fmac_f32_e32 v24, v25, v27
	v_cvt_pk_bf16_f32 v228, v26, v22
	v_cvt_pk_bf16_f32 v229, v23, v24
	s_waitcnt vmcnt(12)
	v_lshlrev_b32_e32 v22, 16, v86
	v_lshlrev_b32_e32 v23, 16, v84
	v_fmac_f32_e32 v22, v14, v23
	v_and_b32_e32 v14, 0xffff0000, v86
	v_and_b32_e32 v23, 0xffff0000, v84
	v_fmac_f32_e32 v14, v15, v23
	v_lshlrev_b32_e32 v15, 16, v87
	v_lshlrev_b32_e32 v23, 16, v85
	v_fmac_f32_e32 v15, v16, v23
	v_and_b32_e32 v16, 0xffff0000, v87
	v_and_b32_e32 v23, 0xffff0000, v85
	v_fmac_f32_e32 v16, v17, v23
	v_cvt_pk_bf16_f32 v230, v22, v14
	v_cvt_pk_bf16_f32 v231, v15, v16
	s_nop 1
	v_permlane16_swap_b32_e32 v224, v226
	v_permlane16_swap_b32_e32 v225, v227
	v_permlane16_swap_b32_e32 v228, v230
	v_permlane16_swap_b32_e32 v229, v231
	v_lshl_add_u64 v[240:241], v[66:67], 0, v[242:243]
	global_store_dwordx4 v[240:241], v[224:227], off sc1
	global_store_dwordx4 v[240:241], v[228:231], off offset:64 sc1
	s_waitcnt vmcnt(9)
	v_lshlrev_b32_e32 v14, 16, v82
	v_lshlrev_b32_e32 v15, 16, v80
	v_fmac_f32_e32 v14, v18, v15
	v_and_b32_e32 v15, 0xffff0000, v82
	v_and_b32_e32 v16, 0xffff0000, v80
	v_fmac_f32_e32 v15, v19, v16
	v_lshlrev_b32_e32 v16, 16, v83
	v_lshlrev_b32_e32 v17, 16, v81
	v_fmac_f32_e32 v16, v20, v17
	v_and_b32_e32 v17, 0xffff0000, v83
	v_and_b32_e32 v18, 0xffff0000, v81
	v_fmac_f32_e32 v17, v21, v18
	v_cvt_pk_bf16_f32 v232, v14, v15
	v_cvt_pk_bf16_f32 v233, v16, v17
	s_waitcnt vmcnt(8)
	v_lshlrev_b32_e32 v14, 16, v78
	v_lshlrev_b32_e32 v15, 16, v76
	v_fmac_f32_e32 v14, v10, v15
	v_and_b32_e32 v10, 0xffff0000, v78
	v_and_b32_e32 v15, 0xffff0000, v76
	v_fmac_f32_e32 v10, v11, v15
	v_lshlrev_b32_e32 v11, 16, v79
	v_lshlrev_b32_e32 v15, 16, v77
	v_fmac_f32_e32 v11, v12, v15
	v_and_b32_e32 v12, 0xffff0000, v79
	v_and_b32_e32 v15, 0xffff0000, v77
	v_fmac_f32_e32 v12, v13, v15
	v_cvt_pk_bf16_f32 v234, v14, v10
	v_cvt_pk_bf16_f32 v235, v11, v12
	s_waitcnt vmcnt(7)
	v_lshlrev_b32_e32 v10, 16, v74
	v_lshlrev_b32_e32 v11, 16, v72
	v_fmac_f32_e32 v10, v6, v11
	v_and_b32_e32 v6, 0xffff0000, v74
	v_and_b32_e32 v11, 0xffff0000, v72
	v_fmac_f32_e32 v6, v7, v11
	v_lshlrev_b32_e32 v7, 16, v75
	v_lshlrev_b32_e32 v11, 16, v73
	v_fmac_f32_e32 v7, v8, v11
	v_and_b32_e32 v8, 0xffff0000, v75
	v_and_b32_e32 v11, 0xffff0000, v73
	v_fmac_f32_e32 v8, v9, v11
	v_cvt_pk_bf16_f32 v236, v10, v6
	v_cvt_pk_bf16_f32 v237, v7, v8
	s_waitcnt vmcnt(6)
	v_lshlrev_b32_e32 v6, 16, v70
	v_lshlrev_b32_e32 v7, 16, v68
	v_fmac_f32_e32 v6, v2, v7
	v_and_b32_e32 v2, 0xffff0000, v70
	v_and_b32_e32 v7, 0xffff0000, v68
	v_fmac_f32_e32 v2, v3, v7
	v_lshlrev_b32_e32 v3, 16, v71
	v_lshlrev_b32_e32 v7, 16, v69
	v_fmac_f32_e32 v3, v4, v7
	v_and_b32_e32 v4, 0xffff0000, v71
	v_and_b32_e32 v7, 0xffff0000, v69
	v_fmac_f32_e32 v4, v5, v7
	v_cvt_pk_bf16_f32 v238, v6, v2
	v_cvt_pk_bf16_f32 v239, v3, v4
	s_nop 1
	v_permlane16_swap_b32_e32 v232, v234
	v_permlane16_swap_b32_e32 v233, v235
	v_permlane16_swap_b32_e32 v236, v238
	v_permlane16_swap_b32_e32 v237, v239
	v_lshl_add_u64 v[240:241], v[66:67], 0, v[242:243]
	global_store_dwordx4 v[240:241], v[232:235], off offset:256 sc1
	global_store_dwordx4 v[240:241], v[236:239], off offset:320 sc1
	s_waitcnt vmcnt(0) lgkmcnt(0)
	s_barrier
	s_and_saveexec_b64 s[50:51], s[4:5]
	s_cbranch_execz .LBB0_281
	s_mov_b64 s[54:55], exec
	v_mbcnt_lo_u32_b32 v2, s54, 0
	v_mbcnt_hi_u32_b32 v2, s55, v2
	v_cmp_eq_u32_e64 s[6:7], 0, v2
	s_and_b64 s[0:1], exec, s[6:7]
	s_mov_b64 exec, s[0:1]
	s_cbranch_execz .LBB0_281
	s_lshl_b32 s0, s48, 4
	s_ashr_i32 s1, s0, 31
	s_lshl_b64 s[0:1], s[0:1], 2
	s_add_u32 s0, s33, s0
	s_addc_u32 s1, s60, s1
	s_bcnt1_i32_b64 s6, s[54:55]
	v_mov_b32_e32 v2, s6
	global_atomic_add v131, v2, s[0:1]
	s_branch .LBB0_281

.LBB0_318:
	s_or_b64 exec, exec, s[46:47]
	v_and_b32_e32 v131, 64, v164
	v_xor_b32_e32 v130, 16, v164
	v_add_u32_e32 v131, 64, v131
	v_cmp_lt_i32_e32 vcc, v130, v131
	v_lshl_or_b32 v150, s16, 8, v1
	v_lshl_or_b32 v152, s38, 8, v147
	v_cndmask_b32_e32 v130, v164, v130, vcc
	v_lshlrev_b32_e32 v167, 2, v130
	v_xor_b32_e32 v130, 32, v164
	v_cmp_lt_i32_e32 vcc, v130, v131
	s_waitcnt vmcnt(0)
	s_barrier
	v_mbcnt_lo_u32_b32 v204, -1, 0
	v_mbcnt_hi_u32_b32 v204, -1, v204
	v_bfe_u32 v204, v204, 4, 1
	v_mul_u32_u24_e32 v204, 24, v204
	v_mov_b32_e32 v205, 0
	v_cndmask_b32_e32 v130, v164, v130, vcc
	v_lshlrev_b32_e32 v166, 2, v130
	v_ashrrev_i32_e32 v151, 31, v150
	s_lshl_b32 s46, s16, 2
	v_ashrrev_i32_e32 v153, 31, v152
	v_readlane_b32 s60, v249, 38
	v_lshlrev_b64 v[130:131], 12, v[152:153]
	v_readlane_b32 s61, v249, 39
	v_lshlrev_b64 v[154:155], 11, v[152:153]
	v_lshl_add_u64 v[154:155], s[12:13], 0, v[154:155]
	v_lshl_add_u64 v[130:131], s[60:61], 0, v[130:131]
	v_lshl_add_u64 v[130:131], v[150:151], 2, v[130:131]
	global_load_dwordx4 v[168:171], v[130:131], off
	global_load_dwordx4 v[172:175], v[130:131], off offset:64
	global_load_dwordx4 v[176:179], v[130:131], off offset:128
	global_load_dwordx4 v[180:183], v[130:131], off offset:192
	global_load_dwordx4 v[142:145], v[130:131], off offset:512
	global_load_dwordx4 v[138:141], v[130:131], off offset:576
	global_load_dwordx4 v[134:137], v[130:131], off offset:640
	s_nop 0
	global_load_dwordx4 v[130:133], v[130:131], off offset:704
	v_lshlrev_b64 v[184:185], 6, v[152:153]
	v_lshl_add_u64 v[154:155], v[150:151], 1, v[154:155]
	v_lshlrev_b32_e32 v148, 2, v146
	v_readlane_b32 s62, v249, 40
	v_readlane_b32 s63, v249, 41
	v_readlane_b32 s64, v249, 42
	v_readlane_b32 s65, v249, 43
	v_readlane_b32 s66, v249, 44
	v_readlane_b32 s67, v249, 45
	v_readlane_b32 s68, v249, 46
	v_readlane_b32 s69, v249, 47
	v_readlane_b32 s70, v249, 48
	v_readlane_b32 s71, v249, 49
	v_readlane_b32 s72, v249, 50
	v_readlane_b32 s73, v249, 51
	v_readlane_b32 s74, v249, 52
	v_readlane_b32 s75, v249, 53
	s_waitcnt vmcnt(7)
	v_pk_add_f32 v[118:119], v[118:119], v[168:169]
	v_pk_add_f32 v[120:121], v[120:121], v[170:171]
	s_waitcnt vmcnt(6)
	v_pk_add_f32 v[122:123], v[122:123], v[172:173]
	v_pk_add_f32 v[124:125], v[124:125], v[174:175]
	s_waitcnt vmcnt(5)
	v_pk_add_f32 v[126:127], v[126:127], v[176:177]
	s_waitcnt vmcnt(4)
	v_pk_add_f32 v[168:169], v[116:117], v[182:183]
	v_pk_mul_f32 v[116:117], v[118:119], v[118:119]
	v_pk_mul_f32 v[170:171], v[120:121], v[120:121]
	v_cvt_pk_bf16_f32 v186, v118, v119
	v_cvt_pk_bf16_f32 v187, v120, v121
	v_pk_mul_f32 v[120:121], v[122:123], v[122:123]
	v_pk_add_f32 v[128:129], v[128:129], v[178:179]
	v_pk_add_f32 v[114:115], v[114:115], v[180:181]
	v_pk_mul_f32 v[172:173], v[124:125], v[124:125]
	v_cvt_pk_bf16_f32 v188, v122, v123
	v_cvt_pk_bf16_f32 v189, v124, v125
	v_pk_mul_f32 v[124:125], v[126:127], v[126:127]
	v_add_f32_e32 v120, v120, v121
	v_add_f32_e32 v116, v116, v117
	v_pk_mul_f32 v[174:175], v[128:129], v[128:129]
	v_cvt_pk_bf16_f32 v190, v126, v127
	v_cvt_pk_bf16_f32 v191, v128, v129
	v_pk_mul_f32 v[128:129], v[114:115], v[114:115]
	v_add_f32_e32 v117, v124, v125
	v_add_f32_e32 v120, v120, v172
	v_add_f32_e32 v116, v116, v170
	v_pk_mul_f32 v[176:177], v[168:169], v[168:169]
	v_add_f32_e32 v121, v128, v129
	v_add_f32_e32 v117, v117, v174
	v_add_f32_e32 v120, v120, v173
	v_add_f32_e32 v116, v116, v171
	v_add_f32_e32 v121, v121, v176
	v_add_f32_e32 v117, v117, v175
	v_add_f32_e32 v116, v116, v120
	v_add_f32_e32 v116, v116, v117
	v_add_f32_e32 v117, v121, v177
	v_add_f32_e32 v116, v116, v117
	ds_bpermute_b32 v117, v167, v116
	v_cvt_pk_bf16_f32 v192, v114, v115
	v_cvt_pk_bf16_f32 v193, v168, v169
	s_nop 1
	v_permlane16_swap_b32_e32 v186, v188
	v_permlane16_swap_b32_e32 v187, v189
	v_permlane16_swap_b32_e32 v190, v192
	v_permlane16_swap_b32_e32 v191, v193
	v_lshl_add_u64 v[202:203], v[154:155], 0, v[204:205]
	global_store_dwordx4 v[202:203], v[186:189], off sc1
	global_store_dwordx4 v[202:203], v[190:193], off offset:64 sc1
	s_waitcnt lgkmcnt(0)
	v_add_f32_e32 v116, v116, v117
	ds_bpermute_b32 v117, v166, v116
	v_lshl_add_u64 v[114:115], s[90:91], 0, v[184:185]
	s_and_saveexec_b64 s[38:39], s[8:9]
	s_cbranch_execz .LBB0_320
	s_lshl_b32 s16, s46, 2
	s_waitcnt lgkmcnt(0)
	v_add_f32_e32 v118, v116, v117
	v_lshl_add_u64 v[116:117], v[114:115], 0, s[16:17]
	v_lshl_add_u64 v[116:117], v[116:117], 0, v[148:149]
	global_store_dword v[116:117], v118, off sc1
.LBB0_320:
	s_or_b64 exec, exec, s[38:39]
	s_waitcnt vmcnt(5)
	v_pk_add_f32 v[110:111], v[110:111], v[142:143]
	v_pk_add_f32 v[112:113], v[112:113], v[144:145]
	s_waitcnt lgkmcnt(0)
	v_pk_mul_f32 v[116:117], v[110:111], v[110:111]
	v_cvt_pk_bf16_f32 v194, v110, v111
	v_cvt_pk_bf16_f32 v195, v112, v113
	s_waitcnt vmcnt(4)
	v_pk_add_f32 v[106:107], v[106:107], v[138:139]
	v_pk_add_f32 v[108:109], v[108:109], v[140:141]
	v_pk_mul_f32 v[110:111], v[106:107], v[106:107]
	v_pk_mul_f32 v[118:119], v[112:113], v[112:113]
	v_pk_mul_f32 v[112:113], v[108:109], v[108:109]
	v_cvt_pk_bf16_f32 v196, v106, v107
	v_add_f32_e32 v107, v110, v111
	v_add_f32_e32 v110, v116, v117
	s_waitcnt vmcnt(3)
	v_pk_add_f32 v[102:103], v[102:103], v[134:135]
	v_add_f32_e32 v107, v107, v112
	v_add_f32_e32 v110, v110, v118
	v_pk_add_f32 v[104:105], v[104:105], v[136:137]
	v_pk_mul_f32 v[120:121], v[102:103], v[102:103]
	s_waitcnt vmcnt(2)
	v_pk_add_f32 v[124:125], v[98:99], v[130:131]
	v_add_f32_e32 v107, v107, v113
	v_add_f32_e32 v110, v110, v119
	v_pk_mul_f32 v[122:123], v[104:105], v[104:105]
	v_pk_add_f32 v[100:101], v[100:101], v[132:133]
	v_pk_mul_f32 v[98:99], v[124:125], v[124:125]
	v_add_f32_e32 v107, v110, v107
	v_add_f32_e32 v110, v120, v121
	v_pk_mul_f32 v[126:127], v[100:101], v[100:101]
	v_add_f32_e32 v110, v110, v122
	v_add_f32_e32 v98, v98, v99
	v_add_f32_e32 v110, v110, v123
	v_add_f32_e32 v98, v98, v126
	v_add_f32_e32 v107, v107, v110
	v_add_f32_e32 v98, v98, v127
	v_add_f32_e32 v98, v107, v98
	ds_bpermute_b32 v99, v167, v98
	v_cvt_pk_bf16_f32 v197, v108, v109
	v_cvt_pk_bf16_f32 v198, v102, v103
	v_cvt_pk_bf16_f32 v199, v104, v105
	s_waitcnt lgkmcnt(0)
	v_add_f32_e32 v98, v98, v99
	ds_bpermute_b32 v99, v166, v98
	v_cvt_pk_bf16_f32 v200, v124, v125
	v_cvt_pk_bf16_f32 v201, v100, v101
	s_nop 1
	v_permlane16_swap_b32_e32 v194, v196
	v_permlane16_swap_b32_e32 v195, v197
	v_permlane16_swap_b32_e32 v198, v200
	v_permlane16_swap_b32_e32 v199, v201
	v_lshl_add_u64 v[202:203], v[154:155], 0, v[204:205]
	global_store_dwordx4 v[202:203], v[194:197], off offset:256 sc1
	global_store_dwordx4 v[202:203], v[198:201], off offset:320 sc1
	s_and_saveexec_b64 s[38:39], s[8:9]
	s_cbranch_execz .LBB0_322
	s_lshl_b32 s16, s46, 2
	s_waitcnt lgkmcnt(0)
	v_add_f32_e32 v100, v98, v99
	v_lshl_add_u64 v[98:99], v[114:115], 0, s[16:17]
	v_lshl_add_u64 v[98:99], v[98:99], 0, v[148:149]
	global_store_dword v[98:99], v100, off offset:8 sc1
.LBB0_322:
	s_or_b64 exec, exec, s[38:39]
	v_add_u32_e32 v114, 16, v152
	v_ashrrev_i32_e32 v115, 31, v114
	v_readlane_b32 s60, v249, 38
	s_waitcnt lgkmcnt(0)
	v_lshlrev_b64 v[98:99], 12, v[114:115]
	v_readlane_b32 s61, v249, 39
	v_lshlrev_b64 v[132:133], 11, v[114:115]
	v_lshlrev_b64 v[134:135], 6, v[114:115]
	v_lshl_add_u64 v[98:99], s[60:61], 0, v[98:99]
	v_lshl_add_u64 v[98:99], v[150:151], 2, v[98:99]
	global_load_dwordx4 v[116:119], v[98:99], off
	global_load_dwordx4 v[120:123], v[98:99], off offset:64
	global_load_dwordx4 v[124:127], v[98:99], off offset:128
	global_load_dwordx4 v[128:131], v[98:99], off offset:192
	global_load_dwordx4 v[110:113], v[98:99], off offset:512
	global_load_dwordx4 v[106:109], v[98:99], off offset:576
	global_load_dwordx4 v[102:105], v[98:99], off offset:640
	s_nop 0
	global_load_dwordx4 v[98:101], v[98:99], off offset:704
	v_lshl_add_u64 v[114:115], s[12:13], 0, v[132:133]
	v_lshl_add_u64 v[114:115], v[150:151], 1, v[114:115]
	v_readlane_b32 s62, v249, 40
	v_readlane_b32 s63, v249, 41
	v_readlane_b32 s64, v249, 42
	v_readlane_b32 s65, v249, 43
	v_readlane_b32 s66, v249, 44
	v_readlane_b32 s67, v249, 45
	v_readlane_b32 s68, v249, 46
	v_readlane_b32 s69, v249, 47
	v_readlane_b32 s70, v249, 48
	v_readlane_b32 s71, v249, 49
	v_readlane_b32 s72, v249, 50
	v_readlane_b32 s73, v249, 51
	v_readlane_b32 s74, v249, 52
	v_readlane_b32 s75, v249, 53
	s_waitcnt vmcnt(7)
	v_pk_add_f32 v[86:87], v[86:87], v[116:117]
	v_pk_add_f32 v[88:89], v[88:89], v[118:119]
	s_waitcnt vmcnt(6)
	v_pk_add_f32 v[90:91], v[90:91], v[120:121]
	v_pk_add_f32 v[92:93], v[92:93], v[122:123]
	s_waitcnt vmcnt(5)
	v_pk_add_f32 v[94:95], v[94:95], v[124:125]
	s_waitcnt vmcnt(4)
	v_pk_add_f32 v[116:117], v[84:85], v[130:131]
	v_pk_mul_f32 v[84:85], v[86:87], v[86:87]
	v_pk_mul_f32 v[118:119], v[88:89], v[88:89]
	v_cvt_pk_bf16_f32 v186, v86, v87
	v_cvt_pk_bf16_f32 v187, v88, v89
	v_pk_mul_f32 v[88:89], v[90:91], v[90:91]
	v_pk_add_f32 v[96:97], v[96:97], v[126:127]
	v_pk_add_f32 v[82:83], v[82:83], v[128:129]
	v_pk_mul_f32 v[120:121], v[92:93], v[92:93]
	v_cvt_pk_bf16_f32 v188, v90, v91
	v_cvt_pk_bf16_f32 v189, v92, v93
	v_pk_mul_f32 v[92:93], v[94:95], v[94:95]
	v_add_f32_e32 v88, v88, v89
	v_add_f32_e32 v84, v84, v85
	v_pk_mul_f32 v[122:123], v[96:97], v[96:97]
	v_pk_mul_f32 v[124:125], v[82:83], v[82:83]
	v_add_f32_e32 v85, v92, v93
	v_add_f32_e32 v88, v88, v120
	v_add_f32_e32 v84, v84, v118
	v_pk_mul_f32 v[126:127], v[116:117], v[116:117]
	v_add_f32_e32 v89, v124, v125
	v_add_f32_e32 v85, v85, v122
	v_add_f32_e32 v88, v88, v121
	v_add_f32_e32 v84, v84, v119
	v_add_f32_e32 v89, v89, v126
	v_add_f32_e32 v85, v85, v123
	v_add_f32_e32 v84, v84, v88
	v_add_f32_e32 v84, v84, v85
	v_add_f32_e32 v85, v89, v127
	v_add_f32_e32 v84, v84, v85
	ds_bpermute_b32 v85, v167, v84
	v_cvt_pk_bf16_f32 v192, v82, v83
	v_cvt_pk_bf16_f32 v193, v116, v117
	v_cvt_pk_bf16_f32 v190, v94, v95
	v_cvt_pk_bf16_f32 v191, v96, v97
	s_waitcnt lgkmcnt(0)
	v_add_f32_e32 v84, v84, v85
	ds_bpermute_b32 v85, v166, v84
	s_nop 1
	v_permlane16_swap_b32_e32 v186, v188
	v_permlane16_swap_b32_e32 v187, v189
	v_permlane16_swap_b32_e32 v190, v192
	v_permlane16_swap_b32_e32 v191, v193
	v_lshl_add_u64 v[202:203], v[114:115], 0, v[204:205]
	global_store_dwordx4 v[202:203], v[186:189], off sc1
	global_store_dwordx4 v[202:203], v[190:193], off offset:64 sc1
	v_lshl_add_u64 v[82:83], s[90:91], 0, v[134:135]
	s_and_saveexec_b64 s[38:39], s[8:9]
	s_cbranch_execz .LBB0_324
	s_lshl_b32 s16, s46, 2
	s_waitcnt lgkmcnt(0)
	v_add_f32_e32 v86, v84, v85
	v_lshl_add_u64 v[84:85], v[82:83], 0, s[16:17]
	v_lshl_add_u64 v[84:85], v[84:85], 0, v[148:149]
	global_store_dword v[84:85], v86, off sc1
.LBB0_324:
	s_or_b64 exec, exec, s[38:39]
	s_waitcnt vmcnt(5)
	v_pk_add_f32 v[78:79], v[78:79], v[110:111]
	v_pk_add_f32 v[80:81], v[80:81], v[112:113]
	s_waitcnt lgkmcnt(0)
	v_pk_mul_f32 v[84:85], v[78:79], v[78:79]
	v_cvt_pk_bf16_f32 v194, v78, v79
	v_cvt_pk_bf16_f32 v195, v80, v81
	s_waitcnt vmcnt(4)
	v_pk_add_f32 v[74:75], v[74:75], v[106:107]
	v_pk_add_f32 v[76:77], v[76:77], v[108:109]
	v_pk_mul_f32 v[78:79], v[74:75], v[74:75]
	v_pk_mul_f32 v[86:87], v[80:81], v[80:81]
	v_pk_mul_f32 v[80:81], v[76:77], v[76:77]
	v_cvt_pk_bf16_f32 v196, v74, v75
	v_add_f32_e32 v75, v78, v79
	v_add_f32_e32 v78, v84, v85
	s_waitcnt vmcnt(3)
	v_pk_add_f32 v[70:71], v[70:71], v[102:103]
	v_add_f32_e32 v75, v75, v80
	v_add_f32_e32 v78, v78, v86
	v_pk_add_f32 v[72:73], v[72:73], v[104:105]
	v_pk_mul_f32 v[88:89], v[70:71], v[70:71]
	s_waitcnt vmcnt(2)
	v_pk_add_f32 v[92:93], v[66:67], v[98:99]
	v_add_f32_e32 v75, v75, v81
	v_add_f32_e32 v78, v78, v87
	v_pk_mul_f32 v[90:91], v[72:73], v[72:73]
	v_pk_add_f32 v[68:69], v[68:69], v[100:101]
	v_pk_mul_f32 v[66:67], v[92:93], v[92:93]
	v_add_f32_e32 v75, v78, v75
	v_add_f32_e32 v78, v88, v89
	v_pk_mul_f32 v[94:95], v[68:69], v[68:69]
	v_add_f32_e32 v78, v78, v90
	v_add_f32_e32 v66, v66, v67
	v_add_f32_e32 v78, v78, v91
	v_add_f32_e32 v66, v66, v94
	v_add_f32_e32 v75, v75, v78
	v_add_f32_e32 v66, v66, v95
	v_add_f32_e32 v66, v75, v66
	ds_bpermute_b32 v67, v167, v66
	v_cvt_pk_bf16_f32 v197, v76, v77
	v_cvt_pk_bf16_f32 v198, v70, v71
	v_cvt_pk_bf16_f32 v199, v72, v73
	s_waitcnt lgkmcnt(0)
	v_add_f32_e32 v66, v66, v67
	ds_bpermute_b32 v67, v166, v66
	v_cvt_pk_bf16_f32 v200, v92, v93
	v_cvt_pk_bf16_f32 v201, v68, v69
	s_nop 1
	v_permlane16_swap_b32_e32 v194, v196
	v_permlane16_swap_b32_e32 v195, v197
	v_permlane16_swap_b32_e32 v198, v200
	v_permlane16_swap_b32_e32 v199, v201
	v_lshl_add_u64 v[202:203], v[114:115], 0, v[204:205]
	global_store_dwordx4 v[202:203], v[194:197], off offset:256 sc1
	global_store_dwordx4 v[202:203], v[198:201], off offset:320 sc1
	s_and_saveexec_b64 s[38:39], s[8:9]
	s_cbranch_execz .LBB0_326
	s_lshl_b32 s16, s46, 2
	s_waitcnt lgkmcnt(0)
	v_add_f32_e32 v68, v66, v67
	v_lshl_add_u64 v[66:67], v[82:83], 0, s[16:17]
	v_lshl_add_u64 v[66:67], v[66:67], 0, v[148:149]
	global_store_dword v[66:67], v68, off offset:8 sc1
.LBB0_326:
	s_or_b64 exec, exec, s[38:39]
	v_add_u32_e32 v82, 0x80, v152
	v_ashrrev_i32_e32 v83, 31, v82
	v_readlane_b32 s60, v249, 38
	s_waitcnt lgkmcnt(0)
	v_lshlrev_b64 v[66:67], 12, v[82:83]
	v_readlane_b32 s61, v249, 39
	v_lshlrev_b64 v[100:101], 11, v[82:83]
	v_lshlrev_b64 v[102:103], 6, v[82:83]
	v_lshl_add_u64 v[66:67], s[60:61], 0, v[66:67]
	v_lshl_add_u64 v[66:67], v[150:151], 2, v[66:67]
	global_load_dwordx4 v[84:87], v[66:67], off
	global_load_dwordx4 v[88:91], v[66:67], off offset:64
	global_load_dwordx4 v[92:95], v[66:67], off offset:128
	global_load_dwordx4 v[96:99], v[66:67], off offset:192
	global_load_dwordx4 v[78:81], v[66:67], off offset:512
	global_load_dwordx4 v[74:77], v[66:67], off offset:576
	global_load_dwordx4 v[70:73], v[66:67], off offset:640
	s_nop 0
	global_load_dwordx4 v[66:69], v[66:67], off offset:704
	v_lshl_add_u64 v[82:83], s[12:13], 0, v[100:101]
	v_lshl_add_u64 v[82:83], v[150:151], 1, v[82:83]
	v_readlane_b32 s62, v249, 40
	v_readlane_b32 s63, v249, 41
	v_readlane_b32 s64, v249, 42
	v_readlane_b32 s65, v249, 43
	v_readlane_b32 s66, v249, 44
	v_readlane_b32 s67, v249, 45
	v_readlane_b32 s68, v249, 46
	v_readlane_b32 s69, v249, 47
	v_readlane_b32 s70, v249, 48
	v_readlane_b32 s71, v249, 49
	v_readlane_b32 s72, v249, 50
	v_readlane_b32 s73, v249, 51
	v_readlane_b32 s74, v249, 52
	v_readlane_b32 s75, v249, 53
	s_waitcnt vmcnt(7)
	v_pk_add_f32 v[54:55], v[54:55], v[84:85]
	v_pk_add_f32 v[56:57], v[56:57], v[86:87]
	s_waitcnt vmcnt(6)
	v_pk_add_f32 v[58:59], v[58:59], v[88:89]
	v_pk_add_f32 v[60:61], v[60:61], v[90:91]
	s_waitcnt vmcnt(5)
	v_pk_add_f32 v[62:63], v[62:63], v[92:93]
	s_waitcnt vmcnt(4)
	v_pk_add_f32 v[84:85], v[52:53], v[98:99]
	v_pk_mul_f32 v[52:53], v[54:55], v[54:55]
	v_pk_mul_f32 v[86:87], v[56:57], v[56:57]
	v_cvt_pk_bf16_f32 v186, v54, v55
	v_cvt_pk_bf16_f32 v187, v56, v57
	v_pk_mul_f32 v[56:57], v[58:59], v[58:59]
	v_pk_add_f32 v[64:65], v[64:65], v[94:95]
	v_pk_add_f32 v[50:51], v[50:51], v[96:97]
	v_pk_mul_f32 v[88:89], v[60:61], v[60:61]
	v_cvt_pk_bf16_f32 v188, v58, v59
	v_cvt_pk_bf16_f32 v189, v60, v61
	v_pk_mul_f32 v[60:61], v[62:63], v[62:63]
	v_add_f32_e32 v56, v56, v57
	v_add_f32_e32 v52, v52, v53
	v_pk_mul_f32 v[90:91], v[64:65], v[64:65]
	v_pk_mul_f32 v[92:93], v[50:51], v[50:51]
	v_add_f32_e32 v53, v60, v61
	v_add_f32_e32 v56, v56, v88
	v_add_f32_e32 v52, v52, v86
	v_pk_mul_f32 v[94:95], v[84:85], v[84:85]
	v_add_f32_e32 v57, v92, v93
	v_add_f32_e32 v53, v53, v90
	v_add_f32_e32 v56, v56, v89
	v_add_f32_e32 v52, v52, v87
	v_add_f32_e32 v57, v57, v94
	v_add_f32_e32 v53, v53, v91
	v_add_f32_e32 v52, v52, v56
	v_add_f32_e32 v52, v52, v53
	v_add_f32_e32 v53, v57, v95
	v_add_f32_e32 v52, v52, v53
	ds_bpermute_b32 v53, v167, v52
	v_cvt_pk_bf16_f32 v192, v50, v51
	v_cvt_pk_bf16_f32 v193, v84, v85
	v_cvt_pk_bf16_f32 v190, v62, v63
	v_cvt_pk_bf16_f32 v191, v64, v65
	s_waitcnt lgkmcnt(0)
	v_add_f32_e32 v52, v52, v53
	ds_bpermute_b32 v53, v166, v52
	s_nop 1
	v_permlane16_swap_b32_e32 v186, v188
	v_permlane16_swap_b32_e32 v187, v189
	v_permlane16_swap_b32_e32 v190, v192
	v_permlane16_swap_b32_e32 v191, v193
	v_lshl_add_u64 v[202:203], v[82:83], 0, v[204:205]
	global_store_dwordx4 v[202:203], v[186:189], off sc1
	global_store_dwordx4 v[202:203], v[190:193], off offset:64 sc1
	v_lshl_add_u64 v[50:51], s[90:91], 0, v[102:103]
	s_and_saveexec_b64 s[38:39], s[8:9]
	s_cbranch_execz .LBB0_328
	s_lshl_b32 s16, s46, 2
	s_waitcnt lgkmcnt(0)
	v_add_f32_e32 v54, v52, v53
	v_lshl_add_u64 v[52:53], v[50:51], 0, s[16:17]
	v_lshl_add_u64 v[52:53], v[52:53], 0, v[148:149]
	global_store_dword v[52:53], v54, off sc1
.LBB0_328:
	s_or_b64 exec, exec, s[38:39]
	s_waitcnt vmcnt(5)
	v_pk_add_f32 v[46:47], v[46:47], v[78:79]
	v_pk_add_f32 v[48:49], v[48:49], v[80:81]
	s_waitcnt lgkmcnt(0)
	v_pk_mul_f32 v[52:53], v[46:47], v[46:47]
	v_cvt_pk_bf16_f32 v194, v46, v47
	v_cvt_pk_bf16_f32 v195, v48, v49
	s_waitcnt vmcnt(4)
	v_pk_add_f32 v[42:43], v[42:43], v[74:75]
	v_pk_add_f32 v[44:45], v[44:45], v[76:77]
	v_pk_mul_f32 v[46:47], v[42:43], v[42:43]
	v_pk_mul_f32 v[54:55], v[48:49], v[48:49]
	v_pk_mul_f32 v[48:49], v[44:45], v[44:45]
	v_cvt_pk_bf16_f32 v196, v42, v43
	v_add_f32_e32 v43, v46, v47
	v_add_f32_e32 v46, v52, v53
	s_waitcnt vmcnt(3)
	v_pk_add_f32 v[38:39], v[38:39], v[70:71]
	v_add_f32_e32 v43, v43, v48
	v_add_f32_e32 v46, v46, v54
	v_pk_add_f32 v[40:41], v[40:41], v[72:73]
	v_pk_mul_f32 v[56:57], v[38:39], v[38:39]
	s_waitcnt vmcnt(2)
	v_pk_add_f32 v[60:61], v[34:35], v[66:67]
	v_add_f32_e32 v43, v43, v49
	v_add_f32_e32 v46, v46, v55
	v_pk_mul_f32 v[58:59], v[40:41], v[40:41]
	v_pk_add_f32 v[36:37], v[36:37], v[68:69]
	v_pk_mul_f32 v[34:35], v[60:61], v[60:61]
	v_add_f32_e32 v43, v46, v43
	v_add_f32_e32 v46, v56, v57
	v_pk_mul_f32 v[62:63], v[36:37], v[36:37]
	v_add_f32_e32 v46, v46, v58
	v_add_f32_e32 v34, v34, v35
	v_add_f32_e32 v46, v46, v59
	v_add_f32_e32 v34, v34, v62
	v_add_f32_e32 v43, v43, v46
	v_add_f32_e32 v34, v34, v63
	v_add_f32_e32 v34, v43, v34
	ds_bpermute_b32 v35, v167, v34
	v_cvt_pk_bf16_f32 v197, v44, v45
	v_cvt_pk_bf16_f32 v198, v38, v39
	v_cvt_pk_bf16_f32 v199, v40, v41
	s_waitcnt lgkmcnt(0)
	v_add_f32_e32 v34, v34, v35
	ds_bpermute_b32 v35, v166, v34
	v_cvt_pk_bf16_f32 v200, v60, v61
	v_cvt_pk_bf16_f32 v201, v36, v37
	s_nop 1
	v_permlane16_swap_b32_e32 v194, v196
	v_permlane16_swap_b32_e32 v195, v197
	v_permlane16_swap_b32_e32 v198, v200
	v_permlane16_swap_b32_e32 v199, v201
	v_lshl_add_u64 v[202:203], v[82:83], 0, v[204:205]
	global_store_dwordx4 v[202:203], v[194:197], off offset:256 sc1
	global_store_dwordx4 v[202:203], v[198:201], off offset:320 sc1
	s_and_saveexec_b64 s[38:39], s[8:9]
	s_cbranch_execz .LBB0_330
	s_lshl_b32 s16, s46, 2
	s_waitcnt lgkmcnt(0)
	v_add_f32_e32 v36, v34, v35
	v_lshl_add_u64 v[34:35], v[50:51], 0, s[16:17]
	v_lshl_add_u64 v[34:35], v[34:35], 0, v[148:149]
	global_store_dword v[34:35], v36, off offset:8 sc1
.LBB0_330:
	s_or_b64 exec, exec, s[38:39]
	v_add_u32_e32 v50, 0x90, v152
	v_ashrrev_i32_e32 v51, 31, v50
	v_readlane_b32 s60, v249, 38
	s_waitcnt lgkmcnt(0)
	v_lshlrev_b64 v[34:35], 12, v[50:51]
	v_readlane_b32 s61, v249, 39
	v_lshlrev_b64 v[68:69], 11, v[50:51]
	v_lshlrev_b64 v[70:71], 6, v[50:51]
	v_lshl_add_u64 v[34:35], s[60:61], 0, v[34:35]
	v_lshl_add_u64 v[34:35], v[150:151], 2, v[34:35]
	global_load_dwordx4 v[52:55], v[34:35], off
	global_load_dwordx4 v[56:59], v[34:35], off offset:64
	global_load_dwordx4 v[60:63], v[34:35], off offset:128
	global_load_dwordx4 v[64:67], v[34:35], off offset:192
	global_load_dwordx4 v[46:49], v[34:35], off offset:512
	global_load_dwordx4 v[42:45], v[34:35], off offset:576
	global_load_dwordx4 v[38:41], v[34:35], off offset:640
	s_nop 0
	global_load_dwordx4 v[34:37], v[34:35], off offset:704
	v_lshl_add_u64 v[50:51], s[12:13], 0, v[68:69]
	v_lshl_add_u64 v[50:51], v[150:151], 1, v[50:51]
	v_readlane_b32 s62, v249, 40
	v_readlane_b32 s63, v249, 41
	v_readlane_b32 s64, v249, 42
	v_readlane_b32 s65, v249, 43
	v_readlane_b32 s66, v249, 44
	v_readlane_b32 s67, v249, 45
	v_readlane_b32 s68, v249, 46
	v_readlane_b32 s69, v249, 47
	v_readlane_b32 s70, v249, 48
	v_readlane_b32 s71, v249, 49
	v_readlane_b32 s72, v249, 50
	v_readlane_b32 s73, v249, 51
	v_readlane_b32 s74, v249, 52
	v_readlane_b32 s75, v249, 53
	s_waitcnt vmcnt(7)
	v_pk_add_f32 v[22:23], v[22:23], v[52:53]
	v_pk_add_f32 v[24:25], v[24:25], v[54:55]
	s_waitcnt vmcnt(6)
	v_pk_add_f32 v[26:27], v[26:27], v[56:57]
	v_pk_add_f32 v[28:29], v[28:29], v[58:59]
	s_waitcnt vmcnt(5)
	v_pk_add_f32 v[30:31], v[30:31], v[60:61]
	s_waitcnt vmcnt(4)
	v_pk_add_f32 v[52:53], v[20:21], v[66:67]
	v_pk_mul_f32 v[20:21], v[22:23], v[22:23]
	v_pk_mul_f32 v[54:55], v[24:25], v[24:25]
	v_cvt_pk_bf16_f32 v186, v22, v23
	v_cvt_pk_bf16_f32 v187, v24, v25
	v_pk_mul_f32 v[24:25], v[26:27], v[26:27]
	v_pk_add_f32 v[32:33], v[32:33], v[62:63]
	v_pk_add_f32 v[18:19], v[18:19], v[64:65]
	v_pk_mul_f32 v[56:57], v[28:29], v[28:29]
	v_cvt_pk_bf16_f32 v188, v26, v27
	v_cvt_pk_bf16_f32 v189, v28, v29
	v_pk_mul_f32 v[28:29], v[30:31], v[30:31]
	v_add_f32_e32 v24, v24, v25
	v_add_f32_e32 v20, v20, v21
	v_pk_mul_f32 v[58:59], v[32:33], v[32:33]
	v_pk_mul_f32 v[60:61], v[18:19], v[18:19]
	v_add_f32_e32 v21, v28, v29
	v_add_f32_e32 v24, v24, v56
	v_add_f32_e32 v20, v20, v54
	v_pk_mul_f32 v[62:63], v[52:53], v[52:53]
	v_add_f32_e32 v25, v60, v61
	v_add_f32_e32 v21, v21, v58
	v_add_f32_e32 v24, v24, v57
	v_add_f32_e32 v20, v20, v55
	v_add_f32_e32 v25, v25, v62
	v_add_f32_e32 v21, v21, v59
	v_add_f32_e32 v20, v20, v24
	v_add_f32_e32 v20, v20, v21
	v_add_f32_e32 v21, v25, v63
	v_add_f32_e32 v20, v20, v21
	ds_bpermute_b32 v21, v167, v20
	v_cvt_pk_bf16_f32 v192, v18, v19
	v_cvt_pk_bf16_f32 v193, v52, v53
	v_cvt_pk_bf16_f32 v190, v30, v31
	v_cvt_pk_bf16_f32 v191, v32, v33
	s_waitcnt lgkmcnt(0)
	v_add_f32_e32 v20, v20, v21
	ds_bpermute_b32 v21, v166, v20
	s_nop 1
	v_permlane16_swap_b32_e32 v186, v188
	v_permlane16_swap_b32_e32 v187, v189
	v_permlane16_swap_b32_e32 v190, v192
	v_permlane16_swap_b32_e32 v191, v193
	v_lshl_add_u64 v[202:203], v[50:51], 0, v[204:205]
	global_store_dwordx4 v[202:203], v[186:189], off sc1
	global_store_dwordx4 v[202:203], v[190:193], off offset:64 sc1
	v_lshl_add_u64 v[18:19], s[90:91], 0, v[70:71]
	s_and_saveexec_b64 s[38:39], s[8:9]
	s_cbranch_execz .LBB0_332
	s_lshl_b32 s16, s46, 2
	s_waitcnt lgkmcnt(0)
	v_add_f32_e32 v22, v20, v21
	v_lshl_add_u64 v[20:21], v[18:19], 0, s[16:17]
	v_lshl_add_u64 v[20:21], v[20:21], 0, v[148:149]
	global_store_dword v[20:21], v22, off sc1
.LBB0_332:
	s_or_b64 exec, exec, s[38:39]
	s_waitcnt vmcnt(5)
	v_pk_add_f32 v[14:15], v[14:15], v[46:47]
	v_pk_add_f32 v[16:17], v[16:17], v[48:49]
	s_waitcnt lgkmcnt(0)
	v_pk_mul_f32 v[20:21], v[14:15], v[14:15]
	v_cvt_pk_bf16_f32 v194, v14, v15
	v_cvt_pk_bf16_f32 v195, v16, v17
	s_waitcnt vmcnt(4)
	v_pk_add_f32 v[10:11], v[10:11], v[42:43]
	v_pk_add_f32 v[12:13], v[12:13], v[44:45]
	v_pk_mul_f32 v[14:15], v[10:11], v[10:11]
	v_pk_mul_f32 v[22:23], v[16:17], v[16:17]
	v_pk_mul_f32 v[16:17], v[12:13], v[12:13]
	v_cvt_pk_bf16_f32 v196, v10, v11
	v_add_f32_e32 v11, v14, v15
	v_add_f32_e32 v14, v20, v21
	s_waitcnt vmcnt(3)
	v_pk_add_f32 v[6:7], v[6:7], v[38:39]
	v_add_f32_e32 v11, v11, v16
	v_add_f32_e32 v14, v14, v22
	v_pk_add_f32 v[8:9], v[8:9], v[40:41]
	v_pk_mul_f32 v[24:25], v[6:7], v[6:7]
	s_waitcnt vmcnt(2)
	v_pk_add_f32 v[28:29], v[2:3], v[34:35]
	v_add_f32_e32 v11, v11, v17
	v_add_f32_e32 v14, v14, v23
	v_pk_mul_f32 v[26:27], v[8:9], v[8:9]
	v_pk_add_f32 v[4:5], v[4:5], v[36:37]
	v_pk_mul_f32 v[2:3], v[28:29], v[28:29]
	v_add_f32_e32 v11, v14, v11
	v_add_f32_e32 v14, v24, v25
	v_pk_mul_f32 v[30:31], v[4:5], v[4:5]
	v_add_f32_e32 v14, v14, v26
	v_add_f32_e32 v2, v2, v3
	v_add_f32_e32 v14, v14, v27
	v_add_f32_e32 v2, v2, v30
	v_add_f32_e32 v11, v11, v14
	v_add_f32_e32 v2, v2, v31
	v_add_f32_e32 v2, v11, v2
	ds_bpermute_b32 v3, v167, v2
	v_cvt_pk_bf16_f32 v197, v12, v13
	v_cvt_pk_bf16_f32 v198, v6, v7
	v_cvt_pk_bf16_f32 v199, v8, v9
	s_waitcnt lgkmcnt(0)
	v_add_f32_e32 v2, v2, v3
	ds_bpermute_b32 v3, v166, v2
	v_cvt_pk_bf16_f32 v200, v28, v29
	v_cvt_pk_bf16_f32 v201, v4, v5
	s_nop 1
	v_permlane16_swap_b32_e32 v194, v196
	v_permlane16_swap_b32_e32 v195, v197
	v_permlane16_swap_b32_e32 v198, v200
	v_permlane16_swap_b32_e32 v199, v201
	v_lshl_add_u64 v[202:203], v[50:51], 0, v[204:205]
	global_store_dwordx4 v[202:203], v[194:197], off offset:256 sc1
	global_store_dwordx4 v[202:203], v[198:201], off offset:320 sc1
	s_and_saveexec_b64 s[38:39], s[8:9]
	s_cbranch_execz .LBB0_334
	s_lshl_b32 s16, s46, 2
	s_waitcnt lgkmcnt(0)
	v_add_f32_e32 v4, v2, v3
	v_lshl_add_u64 v[2:3], v[18:19], 0, s[16:17]
	v_lshl_add_u64 v[2:3], v[2:3], 0, v[148:149]
	global_store_dword v[2:3], v4, off offset:8 sc1
